# v27 + s_setprio 1 for waves 4-7 scoped to the proj GEMM K-loop (reset to 0 at the tile epilogue)
# baseline (speedup 1.0000x reference)
.Lpf_skip_L0:
	s_sub_u32 s4, s4, s81
	s_subb_u32 s5, s5, 0
	s_sub_u32 s0, s0, s81
	s_subb_u32 s1, s1, 0
	s_add_u32 s27, s0, 0xc000
	s_addc_u32 s28, s1, 0
	s_add_u32 s29, s0, 0x8000
	s_addc_u32 s30, s1, 0
	s_add_u32 s31, s0, 0x4000
	s_addc_u32 s34, s1, 0
	s_add_u32 s35, s0, 0x0
	s_addc_u32 s36, s1, 0
	s_add_u32 s37, s4, 0xc000
	s_addc_u32 s39, s5, 0
	s_add_u32 s40, s4, 0x8000
	s_addc_u32 s42, s5, 0
	s_add_u32 s43, s4, 0x4000
	s_addc_u32 s44, s5, 0
	s_add_u32 s45, s4, 0x0
	s_addc_u32 s46, s5, 0
	s_mov_b64 s[0:1], 0
	s_mov_b32 s48, s17
	s_mov_b32 s47, s17
	v_mov_b32_e32 v0, v147
	v_mov_b32_e32 v1, v147
	v_mov_b32_e32 v2, v147
	v_mov_b32_e32 v3, v147
	v_mov_b32_e32 v4, v147
	v_mov_b32_e32 v5, v147
	v_mov_b32_e32 v6, v147
	v_mov_b32_e32 v7, v147
	v_mov_b32_e32 v8, v147
	v_mov_b32_e32 v9, v147
	v_mov_b32_e32 v10, v147
	v_mov_b32_e32 v11, v147
	v_mov_b32_e32 v12, v147
	v_mov_b32_e32 v13, v147
	v_mov_b32_e32 v14, v147
	v_mov_b32_e32 v15, v147
	v_mov_b32_e32 v16, v147
	v_mov_b32_e32 v17, v147
	v_mov_b32_e32 v18, v147
	v_mov_b32_e32 v19, v147
	v_mov_b32_e32 v20, v147
	v_mov_b32_e32 v21, v147
	v_mov_b32_e32 v22, v147
	v_mov_b32_e32 v23, v147
	v_mov_b32_e32 v24, v147
	v_mov_b32_e32 v25, v147
	v_mov_b32_e32 v26, v147
	v_mov_b32_e32 v27, v147
	v_mov_b32_e32 v28, v147
	v_mov_b32_e32 v29, v147
	v_mov_b32_e32 v30, v147
	v_mov_b32_e32 v31, v147
	v_mov_b32_e32 v32, v147
	v_mov_b32_e32 v33, v147
	v_mov_b32_e32 v34, v147
	v_mov_b32_e32 v35, v147
	v_mov_b32_e32 v36, v147
	v_mov_b32_e32 v37, v147
	v_mov_b32_e32 v38, v147
	v_mov_b32_e32 v39, v147
	v_mov_b32_e32 v40, v147
	v_mov_b32_e32 v41, v147
	v_mov_b32_e32 v42, v147
	v_mov_b32_e32 v43, v147
	v_mov_b32_e32 v44, v147
	v_mov_b32_e32 v45, v147
	v_mov_b32_e32 v46, v147
	v_mov_b32_e32 v47, v147
	v_mov_b32_e32 v48, v147
	v_mov_b32_e32 v49, v147
	v_mov_b32_e32 v50, v147
	v_mov_b32_e32 v51, v147
	v_mov_b32_e32 v52, v147
	v_mov_b32_e32 v53, v147
	v_mov_b32_e32 v54, v147
	v_mov_b32_e32 v55, v147
	v_mov_b32_e32 v56, v147
	v_mov_b32_e32 v57, v147
	v_mov_b32_e32 v58, v147
	v_mov_b32_e32 v59, v147
	v_mov_b32_e32 v60, v147
	v_mov_b32_e32 v61, v147
	v_mov_b32_e32 v62, v147
	v_mov_b32_e32 v63, v147
	v_mov_b32_e32 v64, v147
	v_mov_b32_e32 v65, v147
	v_mov_b32_e32 v66, v147
	v_mov_b32_e32 v67, v147
	v_mov_b32_e32 v68, v147
	v_mov_b32_e32 v69, v147
	v_mov_b32_e32 v70, v147
	v_mov_b32_e32 v71, v147
	v_mov_b32_e32 v72, v147
	v_mov_b32_e32 v73, v147
	v_mov_b32_e32 v74, v147
	v_mov_b32_e32 v75, v147
	v_mov_b32_e32 v76, v147
	v_mov_b32_e32 v77, v147
	v_mov_b32_e32 v78, v147
	v_mov_b32_e32 v79, v147
	v_mov_b32_e32 v80, v147
	v_mov_b32_e32 v81, v147
	v_mov_b32_e32 v82, v147
	v_mov_b32_e32 v83, v147
	v_mov_b32_e32 v84, v147
	v_mov_b32_e32 v85, v147
	v_mov_b32_e32 v86, v147
	v_mov_b32_e32 v87, v147
	v_mov_b32_e32 v88, v147
	v_mov_b32_e32 v89, v147
	v_mov_b32_e32 v90, v147
	v_mov_b32_e32 v91, v147
	v_mov_b32_e32 v92, v147
	v_mov_b32_e32 v93, v147
	v_mov_b32_e32 v94, v147
	v_mov_b32_e32 v95, v147
	v_mov_b32_e32 v96, v147
	v_mov_b32_e32 v97, v147
	v_mov_b32_e32 v98, v147
	v_mov_b32_e32 v99, v147
	v_mov_b32_e32 v100, v147
	v_mov_b32_e32 v101, v147
	v_mov_b32_e32 v102, v147
	v_mov_b32_e32 v103, v147
	v_mov_b32_e32 v104, v147
	v_mov_b32_e32 v105, v147
	v_mov_b32_e32 v106, v147
	v_mov_b32_e32 v107, v147
	v_mov_b32_e32 v108, v147
	v_mov_b32_e32 v109, v147
	v_mov_b32_e32 v110, v147
	v_mov_b32_e32 v111, v147
	v_mov_b32_e32 v112, v147
	v_mov_b32_e32 v113, v147
	v_mov_b32_e32 v114, v147
	v_mov_b32_e32 v115, v147
	v_mov_b32_e32 v116, v147
	v_mov_b32_e32 v117, v147
	v_mov_b32_e32 v118, v147
	v_mov_b32_e32 v119, v147
	v_mov_b32_e32 v120, v147
	v_mov_b32_e32 v121, v147
	v_mov_b32_e32 v122, v147
	v_mov_b32_e32 v123, v147
	v_mov_b32_e32 v124, v147
	v_mov_b32_e32 v125, v147
	v_mov_b32_e32 v126, v147
	v_mov_b32_e32 v127, v147
	v_cmp_gt_u32_e32 vcc, 0x100, v178
	s_cbranch_vccnz .Lpr_L0
	s_setprio 1
.Lpr_L0:
	s_cmp_eq_u32 s80, 1
	s_cbranch_scc0 .LBB0_131
	s_mov_b32 s80, 0
	s_waitcnt vmcnt(16)
	s_barrier
	s_branch .Lkin_L0

.LBB0_135:
	s_setprio 0
	s_mov_b32 s98, 0
	s_mov_b32 s99, s68

.Lpf_skip_L1:
	s_sub_u32 s6, s6, s81
	s_subb_u32 s7, s7, 0
	s_sub_u32 s4, s4, s81
	s_subb_u32 s5, s5, 0
	s_add_u32 s27, s4, 0xc000
	s_addc_u32 s28, s5, 0
	s_add_u32 s29, s4, 0x8000
	s_addc_u32 s30, s5, 0
	s_add_u32 s31, s4, 0x4000
	s_addc_u32 s34, s5, 0
	s_add_u32 s35, s4, 0x0
	s_addc_u32 s36, s5, 0
	s_add_u32 s37, s6, 0xc000
	s_addc_u32 s38, s7, 0
	s_add_u32 s39, s6, 0x8000
	s_addc_u32 s40, s7, 0
	s_add_u32 s41, s6, 0x4000
	s_addc_u32 s42, s7, 0
	s_add_u32 s43, s6, 0x0
	s_addc_u32 s44, s7, 0
	s_mov_b64 s[4:5], 0
	s_mov_b32 s46, s17
	s_mov_b32 s45, s17
	v_mov_b32_e32 v0, v145
	v_mov_b32_e32 v1, v145
	v_mov_b32_e32 v2, v145
	v_mov_b32_e32 v3, v145
	v_mov_b32_e32 v4, v145
	v_mov_b32_e32 v5, v145
	v_mov_b32_e32 v6, v145
	v_mov_b32_e32 v7, v145
	v_mov_b32_e32 v8, v145
	v_mov_b32_e32 v9, v145
	v_mov_b32_e32 v10, v145
	v_mov_b32_e32 v11, v145
	v_mov_b32_e32 v12, v145
	v_mov_b32_e32 v13, v145
	v_mov_b32_e32 v14, v145
	v_mov_b32_e32 v15, v145
	v_mov_b32_e32 v16, v145
	v_mov_b32_e32 v17, v145
	v_mov_b32_e32 v18, v145
	v_mov_b32_e32 v19, v145
	v_mov_b32_e32 v20, v145
	v_mov_b32_e32 v21, v145
	v_mov_b32_e32 v22, v145
	v_mov_b32_e32 v23, v145
	v_mov_b32_e32 v24, v145
	v_mov_b32_e32 v25, v145
	v_mov_b32_e32 v26, v145
	v_mov_b32_e32 v27, v145
	v_mov_b32_e32 v28, v145
	v_mov_b32_e32 v29, v145
	v_mov_b32_e32 v30, v145
	v_mov_b32_e32 v31, v145
	v_mov_b32_e32 v32, v145
	v_mov_b32_e32 v33, v145
	v_mov_b32_e32 v34, v145
	v_mov_b32_e32 v35, v145
	v_mov_b32_e32 v36, v145
	v_mov_b32_e32 v37, v145
	v_mov_b32_e32 v38, v145
	v_mov_b32_e32 v39, v145
	v_mov_b32_e32 v40, v145
	v_mov_b32_e32 v41, v145
	v_mov_b32_e32 v42, v145
	v_mov_b32_e32 v43, v145
	v_mov_b32_e32 v44, v145
	v_mov_b32_e32 v45, v145
	v_mov_b32_e32 v46, v145
	v_mov_b32_e32 v47, v145
	v_mov_b32_e32 v48, v145
	v_mov_b32_e32 v49, v145
	v_mov_b32_e32 v50, v145
	v_mov_b32_e32 v51, v145
	v_mov_b32_e32 v52, v145
	v_mov_b32_e32 v53, v145
	v_mov_b32_e32 v54, v145
	v_mov_b32_e32 v55, v145
	v_mov_b32_e32 v56, v145
	v_mov_b32_e32 v57, v145
	v_mov_b32_e32 v58, v145
	v_mov_b32_e32 v59, v145
	v_mov_b32_e32 v60, v145
	v_mov_b32_e32 v61, v145
	v_mov_b32_e32 v62, v145
	v_mov_b32_e32 v63, v145
	v_mov_b32_e32 v64, v145
	v_mov_b32_e32 v65, v145
	v_mov_b32_e32 v66, v145
	v_mov_b32_e32 v67, v145
	v_mov_b32_e32 v68, v145
	v_mov_b32_e32 v69, v145
	v_mov_b32_e32 v70, v145
	v_mov_b32_e32 v71, v145
	v_mov_b32_e32 v72, v145
	v_mov_b32_e32 v73, v145
	v_mov_b32_e32 v74, v145
	v_mov_b32_e32 v75, v145
	v_mov_b32_e32 v76, v145
	v_mov_b32_e32 v77, v145
	v_mov_b32_e32 v78, v145
	v_mov_b32_e32 v79, v145
	v_mov_b32_e32 v80, v145
	v_mov_b32_e32 v81, v145
	v_mov_b32_e32 v82, v145
	v_mov_b32_e32 v83, v145
	v_mov_b32_e32 v84, v145
	v_mov_b32_e32 v85, v145
	v_mov_b32_e32 v86, v145
	v_mov_b32_e32 v87, v145
	v_mov_b32_e32 v88, v145
	v_mov_b32_e32 v89, v145
	v_mov_b32_e32 v90, v145
	v_mov_b32_e32 v91, v145
	v_mov_b32_e32 v92, v145
	v_mov_b32_e32 v93, v145
	v_mov_b32_e32 v94, v145
	v_mov_b32_e32 v95, v145
	v_mov_b32_e32 v96, v145
	v_mov_b32_e32 v97, v145
	v_mov_b32_e32 v98, v145
	v_mov_b32_e32 v99, v145
	v_mov_b32_e32 v100, v145
	v_mov_b32_e32 v101, v145
	v_mov_b32_e32 v102, v145
	v_mov_b32_e32 v103, v145
	v_mov_b32_e32 v104, v145
	v_mov_b32_e32 v105, v145
	v_mov_b32_e32 v106, v145
	v_mov_b32_e32 v107, v145
	v_mov_b32_e32 v108, v145
	v_mov_b32_e32 v109, v145
	v_mov_b32_e32 v110, v145
	v_mov_b32_e32 v111, v145
	v_mov_b32_e32 v112, v145
	v_mov_b32_e32 v113, v145
	v_mov_b32_e32 v114, v145
	v_mov_b32_e32 v115, v145
	v_mov_b32_e32 v116, v145
	v_mov_b32_e32 v117, v145
	v_mov_b32_e32 v118, v145
	v_mov_b32_e32 v119, v145
	v_mov_b32_e32 v120, v145
	v_mov_b32_e32 v121, v145
	v_mov_b32_e32 v122, v145
	v_mov_b32_e32 v123, v145
	v_mov_b32_e32 v124, v145
	v_mov_b32_e32 v125, v145
	v_mov_b32_e32 v126, v145
	v_mov_b32_e32 v127, v145
	v_cmp_gt_u32_e32 vcc, 0x100, v178
	s_cbranch_vccnz .Lpr_L1
	s_setprio 1

.LBB0_730:
	s_setprio 0
	s_mov_b32 s98, 1
	s_mov_b32 s99, s86
